# v50 + softmax K-tile DMA masked (EXEC) to the 64 head dims each pass actually uses: K global->LDS traffic halved
# baseline (speedup 1.0000x reference)
.LBB0_917:
	s_cmp_lt_u32 s94, 3
	s_cselect_b64 s[78:79], -1, 0
	s_and_b64 vcc, exec, s[78:79]
	s_cbranch_vccnz .LBB0_920
	s_add_i32 s3, s33, 0x4000
	s_add_i32 s4, s2, 64
	s_and_b32 s3, s3, 0xc000
	s_lshl_b64 s[12:13], s[4:5], 8
	s_add_i32 s4, s1, s3
	v_subrev_u32_e32 v246, s74, v148
	v_subrev_u32_e32 v247, s76, v150
	s_add_u32 s98, s74, s12
	s_addc_u32 s99, s75, s13
	s_mov_b32 m0, s4
	s_add_i32 s3, s8, s3
	s_mov_b32 exec_lo, 0xff00ff00
	s_mov_b32 exec_hi, 0xff00ff00
	global_load_lds_dwordx4 v246, s[98:99]
	s_add_i32 m0, s4, 0x2000
	s_add_u32 s98, s98, 0x2000
	s_addc_u32 s99, s99, 0
	global_load_lds_dwordx4 v246, s[98:99]
	s_mov_b64 exec, -1
	s_mov_b32 m0, s3
	s_add_u32 s100, s76, s12
	s_addc_u32 s101, s77, s13
	global_load_lds_dwordx4 v247, s[100:101]
	s_add_i32 m0, s3, 0x2000
	s_add_u32 s100, s100, 0x2000
	s_addc_u32 s101, s101, 0
	s_mov_b32 s3, s5
	s_lshl_b64 s[12:13], s[2:3], 8
	s_and_b32 s3, s33, 0xc000
	s_add_i32 s4, s1, s3
	global_load_lds_dwordx4 v247, s[100:101]
	s_add_u32 s98, s74, s12
	s_addc_u32 s99, s75, s13
	s_mov_b32 m0, s4
	s_add_i32 s3, s8, s3
	s_mov_b32 exec_lo, 0xff00ff00
	s_mov_b32 exec_hi, 0xff00ff00
	global_load_lds_dwordx4 v246, s[98:99]
	s_add_i32 m0, s4, 0x2000
	s_add_u32 s98, s98, 0x2000
	s_addc_u32 s99, s99, 0
	global_load_lds_dwordx4 v246, s[98:99]
	s_mov_b64 exec, -1
	s_mov_b32 m0, s3
	s_add_u32 s100, s76, s12
	s_addc_u32 s101, s77, s13
	global_load_lds_dwordx4 v247, s[100:101]
	s_add_i32 m0, s3, 0x2000
	s_add_u32 s100, s100, 0x2000
	s_addc_u32 s101, s101, 0
	global_load_lds_dwordx4 v247, s[100:101]
	s_add_i32 s3, s2, 0xc0
	s_cmp_gt_i32 s3, s90
	s_cbranch_scc0 .LBB0_921

.LBB0_943:
	s_cmp_lt_u32 s92, 3
	s_cselect_b64 s[6:7], -1, 0
	s_and_b64 vcc, exec, s[6:7]
	s_cbranch_vccnz .LBB0_946
	s_add_i32 s3, s0, 0x4000
	s_add_i32 s4, s2, 64
	s_and_b32 s3, s3, 0xc000
	s_lshl_b64 s[12:13], s[4:5], 8
	s_add_i32 s4, s1, s3
	v_subrev_u32_e32 v246, s74, v150
	v_subrev_u32_e32 v247, s76, v152
	s_add_u32 s98, s74, s12
	s_addc_u32 s99, s75, s13
	s_mov_b32 m0, s4
	s_add_i32 s3, s8, s3
	s_mov_b32 exec_lo, 0x00ff00ff
	s_mov_b32 exec_hi, 0x00ff00ff
	global_load_lds_dwordx4 v246, s[98:99]
	s_add_i32 m0, s4, 0x2000
	s_add_u32 s98, s98, 0x2000
	s_addc_u32 s99, s99, 0
	global_load_lds_dwordx4 v246, s[98:99]
	s_mov_b64 exec, -1
	s_mov_b32 m0, s3
	s_add_u32 s100, s76, s12
	s_addc_u32 s101, s77, s13
	global_load_lds_dwordx4 v247, s[100:101]
	s_add_i32 m0, s3, 0x2000
	s_add_u32 s100, s100, 0x2000
	s_addc_u32 s101, s101, 0
	s_mov_b32 s3, s5
	s_lshl_b64 s[12:13], s[2:3], 8
	s_and_b32 s3, s0, 0xc000
	s_add_i32 s4, s1, s3
	global_load_lds_dwordx4 v247, s[100:101]
	s_add_u32 s98, s74, s12
	s_addc_u32 s99, s75, s13
	s_mov_b32 m0, s4
	s_add_i32 s3, s8, s3
	s_mov_b32 exec_lo, 0x00ff00ff
	s_mov_b32 exec_hi, 0x00ff00ff
	global_load_lds_dwordx4 v246, s[98:99]
	s_add_i32 m0, s4, 0x2000
	s_add_u32 s98, s98, 0x2000
	s_addc_u32 s99, s99, 0
	global_load_lds_dwordx4 v246, s[98:99]
	s_mov_b64 exec, -1
	s_mov_b32 m0, s3
	s_add_u32 s100, s76, s12
	s_addc_u32 s101, s77, s13
	global_load_lds_dwordx4 v247, s[100:101]
	s_add_i32 m0, s3, 0x2000
	s_add_u32 s100, s100, 0x2000
	s_addc_u32 s101, s101, 0
	global_load_lds_dwordx4 v247, s[100:101]
	s_add_i32 s3, s2, 0xc0
	s_cmp_gt_i32 s3, s80
	s_cbranch_scc0 .LBB0_947
